# v14 + FFN1-down meta-row skinny GEMM (P2) moved behind the down GEMM units
# baseline (speedup 1.0000x reference)
.LBB0_403:
	s_or_b64 exec, exec, s[2:3]
	s_barrier
.LBB0_408:
	s_mov_b64 s[2:3], s[90:91]
	v_mbcnt_lo_u32_b32 v8, -1, 0
	v_mbcnt_hi_u32_b32 v8, -1, v8
	s_cmpk_lt_i32 s22, 0x400
	v_add_u32_e32 v0, s74, v8
	s_cselect_b64 s[28:29], -1, 0
	s_cmpk_gt_i32 s22, 0x3ff
	v_readfirstlane_b32 s13, v0
	s_cbranch_scc1 .LBB0_438
	s_ashr_i32 s23, s22, 31
	s_load_dwordx2 s[2:3], s[2:3], 0xc8
	s_lshr_b32 s0, s23, 29
	s_add_i32 s7, s22, s0
	s_and_b32 s0, s7, -8
	s_sub_i32 s8, s22, s0
	s_cmp_gt_i32 s8, -1
	s_cbranch_scc0 .LBB0_411
	s_lshl_b32 s6, s8, 7
	s_cbranch_execz .LBB0_412
	s_branch .LBB0_413

.LBB0_438:
	s_mov_b64 s[2:3], s[90:91]
	s_cmpk_gt_i32 s22, 0xff
	v_mbcnt_lo_u32_b32 v0, -1, 0
	v_mbcnt_hi_u32_b32 v0, -1, v0
	s_cbranch_scc1 .Lsk2_done
	v_ashrrev_i32_e32 v1, 4, v0
	s_mul_i32 s0, s81, 0x560
	v_lshlrev_b32_e32 v2, 12, v0
	v_lshl_add_u32 v104, v1, 3, s0
	v_and_b32_e32 v177, 0xf000, v2
	v_lshl_add_u32 v176, v0, 4, 0
	v_lshrrev_b32_e32 v0, 12, v104
	s_mov_b32 s6, 0x40ff000
	v_lshlrev_b32_e32 v60, 2, v1
	v_mul_lo_u32 v0, v0, s6
	v_add_u32_e32 v1, v104, v177
	v_add_lshl_u32 v64, v1, v0, 1
	v_lshlrev_b32_e32 v0, 12, v104
	v_and_b32_e32 v0, 0x7f000000, v0
	v_and_b32_e32 v1, 0xff8, v104
	v_or3_b32 v0, v1, v0, v177
	v_lshlrev_b32_e32 v252, 1, v0
	v_add_u32_e32 v0, 32, v104
	v_lshrrev_b32_e32 v1, 12, v0
	v_mul_lo_u32 v1, v1, s6
	v_add_u32_e32 v2, v0, v177
	v_add_lshl_u32 v74, v2, v1, 1
	v_lshlrev_b32_e32 v1, 12, v0
	v_and_b32_e32 v1, 0x7f000000, v1
	v_and_b32_e32 v0, 0xff8, v0
	v_or3_b32 v0, v0, v1, v177
	v_lshlrev_b32_e32 v206, 1, v0
	v_add_u32_e32 v0, 64, v104
	v_lshrrev_b32_e32 v1, 12, v0
	v_mul_lo_u32 v1, v1, s6
	v_add_u32_e32 v2, v0, v177
	v_add_lshl_u32 v78, v2, v1, 1
	v_lshlrev_b32_e32 v1, 12, v0
	v_and_b32_e32 v1, 0x7f000000, v1
	v_and_b32_e32 v0, 0xff8, v0
	v_or3_b32 v0, v0, v1, v177
	v_lshlrev_b32_e32 v4, 1, v0
	v_add_u32_e32 v0, 0x60, v104
	v_lshrrev_b32_e32 v1, 12, v0
	v_mul_lo_u32 v1, v1, s6
	v_add_u32_e32 v2, v0, v177
	v_add_lshl_u32 v82, v2, v1, 1
	v_lshlrev_b32_e32 v1, 12, v0
	v_and_b32_e32 v1, 0x7f000000, v1
	v_and_b32_e32 v0, 0xff8, v0
	v_or3_b32 v0, v0, v1, v177
	v_lshlrev_b32_e32 v6, 1, v0
	v_add_u32_e32 v0, 0x80, v104
	v_lshrrev_b32_e32 v1, 12, v0
	v_mul_lo_u32 v1, v1, s6
	v_add_u32_e32 v2, v0, v177
	v_add_lshl_u32 v86, v2, v1, 1
	v_lshlrev_b32_e32 v1, 12, v0
	v_and_b32_e32 v1, 0x7f000000, v1
	v_and_b32_e32 v0, 0xff8, v0
	v_or3_b32 v0, v0, v1, v177
	v_lshlrev_b32_e32 v8, 1, v0
	v_add_u32_e32 v0, 0xa0, v104
	v_lshrrev_b32_e32 v1, 12, v0
	v_mul_lo_u32 v1, v1, s6
	v_add_u32_e32 v2, v0, v177
	v_add_lshl_u32 v90, v2, v1, 1
	v_lshlrev_b32_e32 v1, 12, v0
	v_and_b32_e32 v1, 0x7f000000, v1
	v_and_b32_e32 v0, 0xff8, v0
	v_or3_b32 v0, v0, v1, v177
	v_lshlrev_b32_e32 v10, 1, v0
	v_add_u32_e32 v0, 0xc0, v104
	v_lshrrev_b32_e32 v1, 12, v0
	v_mul_lo_u32 v1, v1, s6
	v_add_u32_e32 v2, v0, v177
	v_add_lshl_u32 v94, v2, v1, 1
	v_lshlrev_b32_e32 v1, 12, v0
	v_and_b32_e32 v1, 0x7f000000, v1
	v_and_b32_e32 v0, 0xff8, v0
	v_or3_b32 v0, v0, v1, v177
	v_lshlrev_b32_e32 v12, 1, v0
	v_add_u32_e32 v0, 0xe0, v104
	v_lshrrev_b32_e32 v1, 12, v0
	v_mul_lo_u32 v1, v1, s6
	v_add_u32_e32 v2, v0, v177
	v_add_lshl_u32 v98, v2, v1, 1
	v_lshlrev_b32_e32 v1, 12, v0
	v_and_b32_e32 v1, 0x7f000000, v1
	v_and_b32_e32 v0, 0xff8, v0
	v_or3_b32 v0, v0, v1, v177
	v_lshlrev_b32_e32 v14, 1, v0
	v_add_u32_e32 v0, 0x100, v104
	v_lshrrev_b32_e32 v1, 12, v0
	v_mul_lo_u32 v1, v1, s6
	v_add_u32_e32 v2, v0, v177
	v_add_lshl_u32 v102, v2, v1, 1
	v_lshlrev_b32_e32 v1, 12, v0
	v_and_b32_e32 v1, 0x7f000000, v1
	v_and_b32_e32 v0, 0xff8, v0
	v_or3_b32 v0, v0, v1, v177
	v_lshlrev_b32_e32 v16, 1, v0
	v_add_u32_e32 v0, 0x120, v104
	v_lshrrev_b32_e32 v1, 12, v0
	v_mul_lo_u32 v1, v1, s6
	v_add_u32_e32 v2, v0, v177
	v_add_lshl_u32 v106, v2, v1, 1
	v_lshlrev_b32_e32 v1, 12, v0
	v_and_b32_e32 v1, 0x7f000000, v1
	v_and_b32_e32 v0, 0xff8, v0
	v_or3_b32 v0, v0, v1, v177
	v_lshlrev_b32_e32 v18, 1, v0
	v_add_u32_e32 v0, 0x140, v104
	v_lshrrev_b32_e32 v1, 12, v0
	v_mul_lo_u32 v1, v1, s6
	v_add_u32_e32 v2, v0, v177
	v_add_lshl_u32 v110, v2, v1, 1
	v_lshlrev_b32_e32 v1, 12, v0
	v_and_b32_e32 v1, 0x7f000000, v1
	v_and_b32_e32 v0, 0xff8, v0
	v_or3_b32 v0, v0, v1, v177
	v_lshlrev_b32_e32 v20, 1, v0
	v_add_u32_e32 v0, 0x160, v104
	v_lshrrev_b32_e32 v1, 12, v0
	v_mul_lo_u32 v1, v1, s6
	v_add_u32_e32 v2, v0, v177
	v_add_lshl_u32 v112, v2, v1, 1
	v_lshlrev_b32_e32 v1, 12, v0
	v_and_b32_e32 v1, 0x7f000000, v1
	v_and_b32_e32 v0, 0xff8, v0
	v_or3_b32 v0, v0, v1, v177
	v_lshlrev_b32_e32 v22, 1, v0
	v_add_u32_e32 v0, 0x180, v104
	v_lshrrev_b32_e32 v1, 12, v0
	v_mul_lo_u32 v1, v1, s6
	v_add_u32_e32 v2, v0, v177
	v_add_lshl_u32 v114, v2, v1, 1
	v_lshlrev_b32_e32 v1, 12, v0
	v_and_b32_e32 v1, 0x7f000000, v1
	v_and_b32_e32 v0, 0xff8, v0
	v_or3_b32 v0, v0, v1, v177
	v_lshlrev_b32_e32 v24, 1, v0
	v_add_u32_e32 v0, 0x1a0, v104
	v_lshrrev_b32_e32 v1, 12, v0
	v_mul_lo_u32 v1, v1, s6
	v_add_u32_e32 v2, v0, v177
	v_add_lshl_u32 v116, v2, v1, 1
	v_lshlrev_b32_e32 v1, 12, v0
	v_and_b32_e32 v1, 0x7f000000, v1
	v_and_b32_e32 v0, 0xff8, v0
	v_or3_b32 v0, v0, v1, v177
	v_lshlrev_b32_e32 v26, 1, v0
	v_add_u32_e32 v0, 0x1c0, v104
	v_lshrrev_b32_e32 v1, 12, v0
	v_mul_lo_u32 v1, v1, s6
	v_add_u32_e32 v2, v0, v177
	v_add_lshl_u32 v118, v2, v1, 1
	v_lshlrev_b32_e32 v1, 12, v0
	v_and_b32_e32 v1, 0x7f000000, v1
	v_and_b32_e32 v0, 0xff8, v0
	v_or3_b32 v0, v0, v1, v177
	v_lshlrev_b32_e32 v28, 1, v0
	v_add_u32_e32 v0, 0x1e0, v104
	v_lshrrev_b32_e32 v1, 12, v0
	v_mul_lo_u32 v1, v1, s6
	v_add_u32_e32 v2, v0, v177
	v_add_lshl_u32 v120, v2, v1, 1
	v_lshlrev_b32_e32 v1, 12, v0
	v_and_b32_e32 v1, 0x7f000000, v1
	v_and_b32_e32 v0, 0xff8, v0
	v_or3_b32 v0, v0, v1, v177
	v_lshlrev_b32_e32 v30, 1, v0
	v_add_u32_e32 v0, 0x200, v104
	v_lshrrev_b32_e32 v1, 12, v0
	v_mul_lo_u32 v1, v1, s6
	v_add_u32_e32 v2, v0, v177
	v_add_lshl_u32 v122, v2, v1, 1
	v_lshlrev_b32_e32 v1, 12, v0
	v_and_b32_e32 v1, 0x7f000000, v1
	v_and_b32_e32 v0, 0xff8, v0
	v_or3_b32 v0, v0, v1, v177
	v_lshlrev_b32_e32 v32, 1, v0
	v_add_u32_e32 v0, 0x220, v104
	v_lshrrev_b32_e32 v1, 12, v0
	v_mul_lo_u32 v1, v1, s6
	v_add_u32_e32 v2, v0, v177
	v_add_lshl_u32 v124, v2, v1, 1
	v_lshlrev_b32_e32 v1, 12, v0
	v_and_b32_e32 v1, 0x7f000000, v1
	v_and_b32_e32 v0, 0xff8, v0
	v_or3_b32 v0, v0, v1, v177
	v_lshlrev_b32_e32 v34, 1, v0
	v_add_u32_e32 v0, 0x240, v104
	v_lshrrev_b32_e32 v1, 12, v0
	v_mul_lo_u32 v1, v1, s6
	v_add_u32_e32 v2, v0, v177
	v_add_lshl_u32 v126, v2, v1, 1
	v_lshlrev_b32_e32 v1, 12, v0
	v_and_b32_e32 v1, 0x7f000000, v1
	v_and_b32_e32 v0, 0xff8, v0
	v_or3_b32 v0, v0, v1, v177
	v_lshlrev_b32_e32 v36, 1, v0
	v_add_u32_e32 v0, 0x260, v104
	v_lshrrev_b32_e32 v1, 12, v0
	v_mul_lo_u32 v1, v1, s6
	v_add_u32_e32 v2, v0, v177
	v_add_lshl_u32 v128, v2, v1, 1
	v_lshlrev_b32_e32 v1, 12, v0
	v_and_b32_e32 v1, 0x7f000000, v1
	v_and_b32_e32 v0, 0xff8, v0
	v_or3_b32 v0, v0, v1, v177
	v_lshlrev_b32_e32 v38, 1, v0
	v_add_u32_e32 v0, 0x280, v104
	v_lshrrev_b32_e32 v1, 12, v0
	v_mul_lo_u32 v1, v1, s6
	v_add_u32_e32 v2, v0, v177
	v_add_lshl_u32 v130, v2, v1, 1
	v_lshlrev_b32_e32 v1, 12, v0
	v_and_b32_e32 v1, 0x7f000000, v1
	v_and_b32_e32 v0, 0xff8, v0
	v_add_u32_e32 v58, 0x3a0, v104
	v_or3_b32 v0, v0, v1, v177
	v_lshrrev_b32_e32 v59, 12, v58
	v_lshlrev_b32_e32 v40, 1, v0
	v_add_u32_e32 v0, 0x2a0, v104
	v_mul_lo_u32 v59, v59, s6
	v_add_u32_e32 v62, v58, v177
	v_lshrrev_b32_e32 v1, 12, v0
	v_add_lshl_u32 v148, v62, v59, 1
	v_add_u32_e32 v62, 0x3c0, v104
	v_mul_lo_u32 v1, v1, s6
	v_add_u32_e32 v2, v0, v177
	v_lshrrev_b32_e32 v63, 12, v62
	v_add_lshl_u32 v132, v2, v1, 1
	v_lshlrev_b32_e32 v1, 12, v0
	v_mul_lo_u32 v63, v63, s6
	v_add_u32_e32 v66, v62, v177
	v_and_b32_e32 v1, 0x7f000000, v1
	v_and_b32_e32 v0, 0xff8, v0
	v_add_lshl_u32 v150, v66, v63, 1
	v_add_u32_e32 v66, 0x3e0, v104
	v_or3_b32 v0, v0, v1, v177
	v_lshrrev_b32_e32 v67, 12, v66
	v_lshlrev_b32_e32 v42, 1, v0
	v_add_u32_e32 v0, 0x2c0, v104
	v_mul_lo_u32 v67, v67, s6
	v_add_u32_e32 v68, v66, v177
	v_lshrrev_b32_e32 v1, 12, v0
	v_add_lshl_u32 v152, v68, v67, 1
	v_add_u32_e32 v68, 0x400, v104
	v_mul_lo_u32 v1, v1, s6
	v_add_u32_e32 v2, v0, v177
	v_lshrrev_b32_e32 v69, 12, v68
	v_add_lshl_u32 v134, v2, v1, 1
	v_lshlrev_b32_e32 v1, 12, v0
	v_mul_lo_u32 v69, v69, s6
	v_add_u32_e32 v70, v68, v177
	v_and_b32_e32 v1, 0x7f000000, v1
	v_and_b32_e32 v0, 0xff8, v0
	v_add_lshl_u32 v154, v70, v69, 1
	v_add_u32_e32 v70, 0x420, v104
	v_or3_b32 v0, v0, v1, v177
	v_lshrrev_b32_e32 v71, 12, v70
	v_lshlrev_b32_e32 v44, 1, v0
	v_add_u32_e32 v0, 0x2e0, v104
	v_mul_lo_u32 v71, v71, s6
	v_add_u32_e32 v72, v70, v177
	v_lshrrev_b32_e32 v1, 12, v0
	v_add_lshl_u32 v156, v72, v71, 1
	v_add_u32_e32 v72, 0x440, v104
	v_mul_lo_u32 v1, v1, s6
	v_add_u32_e32 v2, v0, v177
	v_lshrrev_b32_e32 v73, 12, v72
	v_add_lshl_u32 v136, v2, v1, 1
	v_lshlrev_b32_e32 v1, 12, v0
	v_mul_lo_u32 v73, v73, s6
	v_add_u32_e32 v76, v72, v177
	v_and_b32_e32 v1, 0x7f000000, v1
	v_and_b32_e32 v0, 0xff8, v0
	v_add_lshl_u32 v158, v76, v73, 1
	v_add_u32_e32 v76, 0x460, v104
	v_or3_b32 v0, v0, v1, v177
	v_lshrrev_b32_e32 v77, 12, v76
	v_lshlrev_b32_e32 v46, 1, v0
	v_add_u32_e32 v0, 0x300, v104
	v_mul_lo_u32 v77, v77, s6
	v_add_u32_e32 v80, v76, v177
	v_lshrrev_b32_e32 v1, 12, v0
	v_add_lshl_u32 v160, v80, v77, 1
	v_add_u32_e32 v80, 0x480, v104
	v_mul_lo_u32 v1, v1, s6
	v_add_u32_e32 v2, v0, v177
	v_lshrrev_b32_e32 v81, 12, v80
	v_add_lshl_u32 v138, v2, v1, 1
	v_lshlrev_b32_e32 v1, 12, v0
	v_mul_lo_u32 v81, v81, s6
	v_add_u32_e32 v84, v80, v177
	v_and_b32_e32 v1, 0x7f000000, v1
	v_and_b32_e32 v0, 0xff8, v0
	v_add_lshl_u32 v162, v84, v81, 1
	v_add_u32_e32 v84, 0x4a0, v104
	v_or3_b32 v0, v0, v1, v177
	v_lshrrev_b32_e32 v85, 12, v84
	v_lshlrev_b32_e32 v48, 1, v0
	v_add_u32_e32 v0, 0x320, v104
	v_mul_lo_u32 v85, v85, s6
	v_add_u32_e32 v88, v84, v177
	v_lshrrev_b32_e32 v1, 12, v0
	v_add_lshl_u32 v164, v88, v85, 1
	v_add_u32_e32 v88, 0x4c0, v104
	v_mul_lo_u32 v1, v1, s6
	v_add_u32_e32 v2, v0, v177
	v_lshrrev_b32_e32 v89, 12, v88
	v_add_lshl_u32 v140, v2, v1, 1
	v_lshlrev_b32_e32 v1, 12, v0
	v_mul_lo_u32 v89, v89, s6
	v_add_u32_e32 v92, v88, v177
	v_and_b32_e32 v1, 0x7f000000, v1
	v_and_b32_e32 v0, 0xff8, v0
	v_add_lshl_u32 v166, v92, v89, 1
	v_add_u32_e32 v92, 0x4e0, v104
	s_load_dwordx2 s[4:5], s[2:3], 0xc8
	v_or3_b32 v0, v0, v1, v177
	v_lshrrev_b32_e32 v93, 12, v92
	v_lshlrev_b32_e32 v50, 1, v0
	v_add_u32_e32 v0, 0x340, v104
	v_mul_lo_u32 v93, v93, s6
	v_add_u32_e32 v96, v92, v177
	v_lshrrev_b32_e32 v1, 12, v0
	v_add_lshl_u32 v168, v96, v93, 1
	v_add_u32_e32 v96, 0x500, v104
	v_mul_lo_u32 v1, v1, s6
	v_add_u32_e32 v2, v0, v177
	v_lshrrev_b32_e32 v97, 12, v96
	v_add_lshl_u32 v142, v2, v1, 1
	v_lshlrev_b32_e32 v1, 12, v0
	v_mul_lo_u32 v97, v97, s6
	v_add_u32_e32 v100, v96, v177
	s_waitcnt lgkmcnt(0)
	s_add_u32 s8, s4, 0xb400000
	v_and_b32_e32 v1, 0x7f000000, v1
	v_and_b32_e32 v0, 0xff8, v0
	v_add_u32_e32 v2, 0x360, v104
	v_add_lshl_u32 v170, v100, v97, 1
	v_add_u32_e32 v100, 0x520, v104
	s_addc_u32 s9, s5, 0
	s_lshl_b32 s10, s81, 10
	v_or3_b32 v0, v0, v1, v177
	v_lshlrev_b32_e32 v3, 12, v2
	v_lshrrev_b32_e32 v101, 12, v100
	s_cmp_lt_u32 s61, 64
	v_lshlrev_b32_e32 v52, 1, v0
	v_lshrrev_b32_e32 v0, 12, v2
	v_add_u32_e32 v1, v2, v177
	v_and_b32_e32 v3, 0x7f000000, v3
	v_and_b32_e32 v2, 0xff8, v2
	v_add_u32_e32 v56, 0x380, v104
	v_mul_lo_u32 v101, v101, s6
	v_add_u32_e32 v105, v100, v177
	v_add_u32_e32 v104, 0x540, v104
	s_cselect_b64 s[2:3], -1, 0
	v_or3_b32 v2, v2, v3, v177
	v_add_lshl_u32 v172, v105, v101, 1
	v_lshrrev_b32_e32 v105, 12, v104
	s_add_u32 s0, s4, 0x37a00000
	v_mov_b32_e32 v65, 0
	v_mul_lo_u32 v0, v0, s6
	v_lshlrev_b32_e32 v54, 1, v2
	v_lshrrev_b32_e32 v2, 12, v56
	v_mul_lo_u32 v105, v105, s6
	v_add_u32_e32 v108, v104, v177
	s_addc_u32 s1, s5, 0
	v_add_lshl_u32 v0, v1, v0, 1
	v_mov_b32_e32 v1, v65
	v_mul_lo_u32 v2, v2, s6
	v_add_u32_e32 v3, v56, v177
	v_lshlrev_b32_e32 v57, 12, v56
	v_lshlrev_b32_e32 v59, 12, v58
	v_lshlrev_b32_e32 v63, 12, v62
	v_lshlrev_b32_e32 v67, 12, v66
	v_lshlrev_b32_e32 v69, 12, v68
	v_lshlrev_b32_e32 v71, 12, v70
	v_lshlrev_b32_e32 v73, 12, v72
	v_lshlrev_b32_e32 v77, 12, v76
	v_lshlrev_b32_e32 v81, 12, v80
	v_lshlrev_b32_e32 v85, 12, v84
	v_lshlrev_b32_e32 v89, 12, v88
	v_lshlrev_b32_e32 v93, 12, v92
	v_lshlrev_b32_e32 v97, 12, v96
	v_lshlrev_b32_e32 v101, 12, v100
	v_add_lshl_u32 v174, v108, v105, 1
	v_lshlrev_b32_e32 v105, 12, v104
	v_lshl_add_u64 v[108:109], s[0:1], 0, v[64:65]
	v_lshlrev_b32_e32 v64, 1, v177
	v_ashrrev_i32_e32 v61, 31, v60
	v_mov_b32_e32 v75, v65
	v_mov_b32_e32 v79, v65
	v_mov_b32_e32 v83, v65
	v_mov_b32_e32 v87, v65
	v_mov_b32_e32 v91, v65
	v_mov_b32_e32 v95, v65
	v_mov_b32_e32 v99, v65
	v_mov_b32_e32 v103, v65
	v_mov_b32_e32 v107, v65
	v_mov_b32_e32 v111, v65
	v_mov_b32_e32 v113, v65
	v_mov_b32_e32 v115, v65
	v_mov_b32_e32 v117, v65
	v_mov_b32_e32 v119, v65
	v_mov_b32_e32 v121, v65
	v_mov_b32_e32 v123, v65
	v_mov_b32_e32 v125, v65
	v_mov_b32_e32 v127, v65
	v_mov_b32_e32 v129, v65
	v_mov_b32_e32 v131, v65
	v_mov_b32_e32 v133, v65
	v_mov_b32_e32 v135, v65
	v_mov_b32_e32 v137, v65
	v_mov_b32_e32 v139, v65
	v_mov_b32_e32 v141, v65
	v_mov_b32_e32 v143, v65
	v_add_lshl_u32 v2, v3, v2, 1
	v_mov_b32_e32 v3, v65
	v_and_b32_e32 v57, 0x7f000000, v57
	v_and_b32_e32 v56, 0xff8, v56
	v_mov_b32_e32 v149, v65
	v_and_b32_e32 v59, 0x7f000000, v59
	v_and_b32_e32 v58, 0xff8, v58
	v_mov_b32_e32 v151, v65
	v_and_b32_e32 v63, 0x7f000000, v63
	v_and_b32_e32 v62, 0xff8, v62
	v_mov_b32_e32 v153, v65
	v_and_b32_e32 v67, 0x7f000000, v67
	v_and_b32_e32 v66, 0xff8, v66
	v_mov_b32_e32 v155, v65
	v_and_b32_e32 v69, 0x7f000000, v69
	v_and_b32_e32 v68, 0xff8, v68
	v_mov_b32_e32 v157, v65
	v_and_b32_e32 v71, 0x7f000000, v71
	v_and_b32_e32 v70, 0xff8, v70
	v_mov_b32_e32 v159, v65
	v_and_b32_e32 v73, 0x7f000000, v73
	v_and_b32_e32 v72, 0xff8, v72
	v_mov_b32_e32 v161, v65
	v_and_b32_e32 v77, 0x7f000000, v77
	v_and_b32_e32 v76, 0xff8, v76
	v_mov_b32_e32 v163, v65
	v_and_b32_e32 v81, 0x7f000000, v81
	v_and_b32_e32 v80, 0xff8, v80
	v_mov_b32_e32 v165, v65
	v_and_b32_e32 v85, 0x7f000000, v85
	v_and_b32_e32 v84, 0xff8, v84
	v_mov_b32_e32 v167, v65
	v_and_b32_e32 v89, 0x7f000000, v89
	v_and_b32_e32 v88, 0xff8, v88
	v_mov_b32_e32 v169, v65
	v_and_b32_e32 v93, 0x7f000000, v93
	v_and_b32_e32 v92, 0xff8, v92
	v_mov_b32_e32 v171, v65
	v_and_b32_e32 v97, 0x7f000000, v97
	v_and_b32_e32 v96, 0xff8, v96
	v_mov_b32_e32 v173, v65
	v_and_b32_e32 v101, 0x7f000000, v101
	v_and_b32_e32 v100, 0xff8, v100
	v_mov_b32_e32 v175, v65
	v_and_b32_e32 v105, 0x7f000000, v105
	v_and_b32_e32 v104, 0xff8, v104
	v_lshl_add_u64 v[144:145], s[0:1], 0, v[0:1]
	v_lshl_add_u64 v[0:1], s[4:5], 0, v[64:65]
	v_or3_b32 v56, v56, v57, v177
	v_or3_b32 v58, v58, v59, v177
	v_or3_b32 v62, v62, v63, v177
	v_or3_b32 v66, v66, v67, v177
	v_or3_b32 v68, v68, v69, v177
	v_or3_b32 v70, v70, v71, v177
	v_or3_b32 v72, v72, v73, v177
	v_or3_b32 v76, v76, v77, v177
	v_or3_b32 v80, v80, v81, v177
	v_or3_b32 v84, v84, v85, v177
	v_or3_b32 v88, v88, v89, v177
	v_or3_b32 v92, v92, v93, v177
	v_or3_b32 v96, v96, v97, v177
	v_or3_b32 v100, v100, v101, v177
	v_or3_b32 v104, v104, v105, v177
	v_lshl_add_u64 v[74:75], s[0:1], 0, v[74:75]
	v_lshl_add_u64 v[78:79], s[0:1], 0, v[78:79]
	v_lshl_add_u64 v[82:83], s[0:1], 0, v[82:83]
	v_lshl_add_u64 v[86:87], s[0:1], 0, v[86:87]
	v_lshl_add_u64 v[90:91], s[0:1], 0, v[90:91]
	v_lshl_add_u64 v[94:95], s[0:1], 0, v[94:95]
	v_lshl_add_u64 v[98:99], s[0:1], 0, v[98:99]
	v_lshl_add_u64 v[102:103], s[0:1], 0, v[102:103]
	v_lshl_add_u64 v[106:107], s[0:1], 0, v[106:107]
	v_lshl_add_u64 v[110:111], s[0:1], 0, v[110:111]
	v_lshl_add_u64 v[112:113], s[0:1], 0, v[112:113]
	v_lshl_add_u64 v[114:115], s[0:1], 0, v[114:115]
	v_lshl_add_u64 v[116:117], s[0:1], 0, v[116:117]
	v_lshl_add_u64 v[118:119], s[0:1], 0, v[118:119]
	v_lshl_add_u64 v[120:121], s[0:1], 0, v[120:121]
	v_lshl_add_u64 v[122:123], s[0:1], 0, v[122:123]
	v_lshl_add_u64 v[124:125], s[0:1], 0, v[124:125]
	v_lshl_add_u64 v[126:127], s[0:1], 0, v[126:127]
	v_lshl_add_u64 v[128:129], s[0:1], 0, v[128:129]
	v_lshl_add_u64 v[130:131], s[0:1], 0, v[130:131]
	v_lshl_add_u64 v[132:133], s[0:1], 0, v[132:133]
	v_lshl_add_u64 v[134:135], s[0:1], 0, v[134:135]
	v_lshl_add_u64 v[136:137], s[0:1], 0, v[136:137]
	v_lshl_add_u64 v[138:139], s[0:1], 0, v[138:139]
	v_lshl_add_u64 v[140:141], s[0:1], 0, v[140:141]
	v_lshl_add_u64 v[142:143], s[0:1], 0, v[142:143]
	v_lshl_add_u64 v[146:147], s[0:1], 0, v[2:3]
	v_lshl_add_u64 v[148:149], s[0:1], 0, v[148:149]
	v_lshl_add_u64 v[150:151], s[0:1], 0, v[150:151]
	v_lshl_add_u64 v[152:153], s[0:1], 0, v[152:153]
	v_lshl_add_u64 v[154:155], s[0:1], 0, v[154:155]
	v_lshl_add_u64 v[156:157], s[0:1], 0, v[156:157]
	v_lshl_add_u64 v[158:159], s[0:1], 0, v[158:159]
	v_lshl_add_u64 v[160:161], s[0:1], 0, v[160:161]
	v_lshl_add_u64 v[162:163], s[0:1], 0, v[162:163]
	v_lshl_add_u64 v[164:165], s[0:1], 0, v[164:165]
	v_lshl_add_u64 v[166:167], s[0:1], 0, v[166:167]
	v_lshl_add_u64 v[168:169], s[0:1], 0, v[168:169]
	v_lshl_add_u64 v[170:171], s[0:1], 0, v[170:171]
	v_lshl_add_u64 v[172:173], s[0:1], 0, v[172:173]
	v_lshl_add_u64 v[174:175], s[0:1], 0, v[174:175]
	v_lshl_add_u64 v[0:1], v[60:61], 1, v[0:1]
	s_mov_b64 s[0:1], 0x2f800000
	v_mov_b32_e32 v253, v65
	v_mov_b32_e32 v207, v65
	v_mov_b32_e32 v5, v65
	v_mov_b32_e32 v7, v65
	v_mov_b32_e32 v9, v65
	v_mov_b32_e32 v11, v65
	v_mov_b32_e32 v13, v65
	v_mov_b32_e32 v15, v65
	v_mov_b32_e32 v17, v65
	v_mov_b32_e32 v19, v65
	v_mov_b32_e32 v21, v65
	v_mov_b32_e32 v23, v65
	v_mov_b32_e32 v25, v65
	v_mov_b32_e32 v27, v65
	v_mov_b32_e32 v29, v65
	v_mov_b32_e32 v31, v65
	v_mov_b32_e32 v33, v65
	v_mov_b32_e32 v35, v65
	v_mov_b32_e32 v37, v65
	v_mov_b32_e32 v39, v65
	v_mov_b32_e32 v41, v65
	v_mov_b32_e32 v43, v65
	v_mov_b32_e32 v45, v65
	v_mov_b32_e32 v47, v65
	v_mov_b32_e32 v49, v65
	v_mov_b32_e32 v51, v65
	v_mov_b32_e32 v53, v65
	v_mov_b32_e32 v55, v65
	v_lshlrev_b32_e32 v56, 1, v56
	v_mov_b32_e32 v57, v65
	v_lshlrev_b32_e32 v58, 1, v58
	v_mov_b32_e32 v59, v65
	v_lshlrev_b32_e32 v62, 1, v62
	v_mov_b32_e32 v63, v65
	v_lshlrev_b32_e32 v66, 1, v66
	v_mov_b32_e32 v67, v65
	v_lshlrev_b32_e32 v68, 1, v68
	v_mov_b32_e32 v69, v65
	v_lshlrev_b32_e32 v70, 1, v70
	v_mov_b32_e32 v71, v65
	v_lshlrev_b32_e32 v72, 1, v72
	v_mov_b32_e32 v73, v65
	v_lshlrev_b32_e32 v76, 1, v76
	v_mov_b32_e32 v77, v65
	v_lshlrev_b32_e32 v80, 1, v80
	v_mov_b32_e32 v81, v65
	v_lshlrev_b32_e32 v84, 1, v84
	v_mov_b32_e32 v85, v65
	v_lshlrev_b32_e32 v88, 1, v88
	v_mov_b32_e32 v89, v65
	v_lshlrev_b32_e32 v92, 1, v92
	v_mov_b32_e32 v93, v65
	v_lshlrev_b32_e32 v96, 1, v96
	v_mov_b32_e32 v97, v65
	v_lshlrev_b32_e32 v100, 1, v100
	v_mov_b32_e32 v101, v65
	v_lshlrev_b32_e32 v104, 1, v104
	v_mov_b32_e32 v105, v65
	v_lshl_add_u64 v[60:61], v[0:1], 0, s[0:1]
	s_lshl_b32 s4, s22, 4
	s_lshl_b32 s11, s72, 4
	s_movk_i32 s12, 0x7fff
	s_mov_b32 s13, 0xffff0000
	s_mov_b32 s14, s22
	s_branch .LBB0_406

.LBB0_406:
	s_ashr_i32 s5, s4, 31
	s_lshl_b64 s[0:1], s[4:5], 13
	s_add_u32 s6, s8, s0
	s_addc_u32 s7, s9, s1
	v_lshl_add_u64 v[0:1], s[6:7], 0, v[252:253]
	global_load_dwordx4 v[178:181], v[0:1], off
	v_lshl_add_u64 v[0:1], s[6:7], 0, v[206:207]
	global_load_dwordx4 v[182:185], v[0:1], off
	global_load_dwordx4 v[186:189], v[108:109], off
	global_load_dwordx4 v[190:193], v[74:75], off
	v_lshl_add_u64 v[0:1], s[6:7], 0, v[4:5]
	global_load_dwordx4 v[194:197], v[0:1], off
	v_lshl_add_u64 v[0:1], s[6:7], 0, v[6:7]
	global_load_dwordx4 v[198:201], v[0:1], off
	global_load_dwordx4 v[202:205], v[78:79], off
	global_load_dwordx4 v[208:211], v[82:83], off
	v_lshl_add_u64 v[0:1], s[6:7], 0, v[8:9]
	global_load_dwordx4 v[212:215], v[0:1], off
	global_load_dwordx4 v[216:219], v[86:87], off
	v_lshl_add_u64 v[0:1], s[6:7], 0, v[10:11]
	global_load_dwordx4 v[220:223], v[0:1], off
	global_load_dwordx4 v[224:227], v[90:91], off
	v_lshl_add_u64 v[0:1], s[6:7], 0, v[12:13]
	global_load_dwordx4 v[228:231], v[0:1], off
	v_lshl_add_u64 v[0:1], s[6:7], 0, v[14:15]
	global_load_dwordx4 v[232:235], v[0:1], off
	global_load_dwordx4 v[236:239], v[94:95], off
	global_load_dwordx4 v[240:243], v[98:99], off
	v_lshl_add_u64 v[0:1], s[6:7], 0, v[16:17]
	global_load_dwordx4 v[244:247], v[0:1], off
	global_load_dwordx4 v[248:251], v[174:175], off
	v_lshl_add_u64 v[0:1], s[6:7], 0, v[18:19]
	global_load_dwordx4 v[0:3], v[0:1], off
	v_lshl_add_u64 v[64:65], s[6:7], 0, v[20:21]
	s_andn2_b64 vcc, exec, s[2:3]
	s_waitcnt vmcnt(16)
	v_mfma_f32_16x16x32_bf16 v[178:181], v[178:181], v[186:189], 0
	global_load_dwordx4 v[186:189], v[102:103], off
	s_waitcnt vmcnt(16)
	v_mfma_f32_16x16x32_bf16 v[178:181], v[182:185], v[190:193], v[178:181]
	global_load_dwordx4 v[182:185], v[106:107], off
	global_load_dwordx4 v[190:193], v[64:65], off
	v_lshl_add_u64 v[64:65], s[6:7], 0, v[22:23]
	s_waitcnt vmcnt(15)
	v_mfma_f32_16x16x32_bf16 v[178:181], v[194:197], v[202:205], v[178:181]
	global_load_dwordx4 v[194:197], v[110:111], off
	global_load_dwordx4 v[202:205], v[64:65], off
	v_lshl_add_u64 v[64:65], s[6:7], 0, v[24:25]
	s_waitcnt vmcnt(16)
	v_mfma_f32_16x16x32_bf16 v[178:181], v[198:201], v[208:211], v[178:181]
	global_load_dwordx4 v[198:201], v[112:113], off
	global_load_dwordx4 v[208:211], v[64:65], off
	v_lshl_add_u64 v[64:65], s[6:7], 0, v[26:27]
	s_waitcnt vmcnt(16)
	v_mfma_f32_16x16x32_bf16 v[178:181], v[212:215], v[216:219], v[178:181]
	global_load_dwordx4 v[212:215], v[114:115], off
	global_load_dwordx4 v[216:219], v[64:65], off
	v_lshl_add_u64 v[64:65], s[6:7], 0, v[28:29]
	s_waitcnt vmcnt(16)
	v_mfma_f32_16x16x32_bf16 v[178:181], v[220:223], v[224:227], v[178:181]
	global_load_dwordx4 v[220:223], v[116:117], off
	global_load_dwordx4 v[224:227], v[64:65], off
	v_lshl_add_u64 v[64:65], s[6:7], 0, v[30:31]
	s_waitcnt vmcnt(15)
	v_mfma_f32_16x16x32_bf16 v[178:181], v[228:231], v[236:239], v[178:181]
	global_load_dwordx4 v[228:231], v[64:65], off
	v_lshl_add_u64 v[64:65], s[6:7], 0, v[32:33]
	s_waitcnt vmcnt(15)
	v_mfma_f32_16x16x32_bf16 v[178:181], v[232:235], v[240:243], v[178:181]
	global_load_dwordx4 v[232:235], v[118:119], off
	global_load_dwordx4 v[236:239], v[120:121], off
	s_waitcnt vmcnt(13)
	v_mfma_f32_16x16x32_bf16 v[178:181], v[244:247], v[186:189], v[178:181]
	global_load_dwordx4 v[186:189], v[64:65], off
	v_lshl_add_u64 v[64:65], s[6:7], 0, v[34:35]
	global_load_dwordx4 v[240:243], v[64:65], off
	s_waitcnt vmcnt(14)
	v_mfma_f32_16x16x32_bf16 v[0:3], v[0:3], v[182:185], v[178:181]
	s_nop 2
	global_load_dwordx4 v[178:181], v[122:123], off
	global_load_dwordx4 v[182:185], v[124:125], off
	v_lshl_add_u64 v[64:65], s[6:7], 0, v[36:37]
	s_waitcnt vmcnt(14)
	v_mfma_f32_16x16x32_bf16 v[0:3], v[190:193], v[194:197], v[0:3]
	global_load_dwordx4 v[190:193], v[64:65], off
	v_lshl_add_u64 v[64:65], s[6:7], 0, v[38:39]
	global_load_dwordx4 v[194:197], v[64:65], off
	s_waitcnt vmcnt(14)
	v_mfma_f32_16x16x32_bf16 v[0:3], v[202:205], v[198:201], v[0:3]
	global_load_dwordx4 v[198:201], v[126:127], off
	global_load_dwordx4 v[202:205], v[128:129], off
	v_lshl_add_u64 v[64:65], s[6:7], 0, v[40:41]
	s_waitcnt vmcnt(14)
	v_mfma_f32_16x16x32_bf16 v[0:3], v[208:211], v[212:215], v[0:3]
	global_load_dwordx4 v[208:211], v[64:65], off
	global_load_dwordx4 v[212:215], v[130:131], off
	v_lshl_add_u64 v[64:65], s[6:7], 0, v[42:43]
	s_waitcnt vmcnt(14)
	v_mfma_f32_16x16x32_bf16 v[0:3], v[216:219], v[220:223], v[0:3]
	global_load_dwordx4 v[216:219], v[64:65], off
	global_load_dwordx4 v[220:223], v[132:133], off
	v_lshl_add_u64 v[64:65], s[6:7], 0, v[44:45]
	s_waitcnt vmcnt(13)
	v_mfma_f32_16x16x32_bf16 v[0:3], v[224:227], v[232:235], v[0:3]
	global_load_dwordx4 v[224:227], v[64:65], off
	v_lshl_add_u64 v[64:65], s[6:7], 0, v[46:47]
	s_waitcnt vmcnt(13)
	v_mfma_f32_16x16x32_bf16 v[0:3], v[228:231], v[236:239], v[0:3]
	global_load_dwordx4 v[228:231], v[64:65], off
	v_lshl_add_u64 v[64:65], s[6:7], 0, v[48:49]
	s_waitcnt vmcnt(11)
	v_mfma_f32_16x16x32_bf16 v[0:3], v[186:189], v[178:181], v[0:3]
	global_load_dwordx4 v[178:181], v[134:135], off
	global_load_dwordx4 v[186:189], v[136:137], off
	s_waitcnt vmcnt(12)
	v_mfma_f32_16x16x32_bf16 v[0:3], v[240:243], v[182:185], v[0:3]
	global_load_dwordx4 v[182:185], v[64:65], off
	v_lshl_add_u64 v[64:65], s[6:7], 0, v[50:51]
	global_load_dwordx4 v[232:235], v[64:65], off
	s_waitcnt vmcnt(11)
	v_mfma_f32_16x16x32_bf16 v[0:3], v[190:193], v[198:201], v[0:3]
	global_load_dwordx4 v[190:193], v[138:139], off
	global_load_dwordx4 v[198:201], v[140:141], off
	v_lshl_add_u64 v[64:65], s[6:7], 0, v[52:53]
	s_waitcnt vmcnt(12)
	v_mfma_f32_16x16x32_bf16 v[0:3], v[194:197], v[202:205], v[0:3]
	global_load_dwordx4 v[194:197], v[64:65], off
	global_load_dwordx4 v[202:205], v[142:143], off
	v_lshl_add_u64 v[64:65], s[6:7], 0, v[54:55]
	s_waitcnt vmcnt(12)
	v_mfma_f32_16x16x32_bf16 v[0:3], v[208:211], v[212:215], v[0:3]
	global_load_dwordx4 v[208:211], v[64:65], off
	global_load_dwordx4 v[212:215], v[144:145], off
	v_lshl_add_u64 v[64:65], s[6:7], 0, v[56:57]
	s_waitcnt vmcnt(12)
	v_mfma_f32_16x16x32_bf16 v[0:3], v[216:219], v[220:223], v[0:3]
	s_waitcnt vmcnt(9)
	v_mfma_f32_16x16x32_bf16 v[0:3], v[224:227], v[178:181], v[0:3]
	global_load_dwordx4 v[178:181], v[64:65], off
	v_lshl_add_u64 v[64:65], s[6:7], 0, v[58:59]
	global_load_dwordx4 v[216:219], v[64:65], off
	s_waitcnt vmcnt(10)
	v_mfma_f32_16x16x32_bf16 v[0:3], v[228:231], v[186:189], v[0:3]
	global_load_dwordx4 v[186:189], v[146:147], off
	global_load_dwordx4 v[220:223], v[148:149], off
	v_lshl_add_u64 v[64:65], s[6:7], 0, v[62:63]
	s_waitcnt vmcnt(9)
	v_mfma_f32_16x16x32_bf16 v[0:3], v[182:185], v[190:193], v[0:3]
	global_load_dwordx4 v[182:185], v[64:65], off
	global_load_dwordx4 v[190:193], v[150:151], off
	v_lshl_add_u64 v[64:65], s[6:7], 0, v[66:67]
	s_waitcnt vmcnt(10)
	v_mfma_f32_16x16x32_bf16 v[0:3], v[232:235], v[198:201], v[0:3]
	global_load_dwordx4 v[198:201], v[64:65], off
	s_waitcnt vmcnt(9)
	v_mfma_f32_16x16x32_bf16 v[0:3], v[194:197], v[202:205], v[0:3]
	global_load_dwordx4 v[194:197], v[152:153], off
	v_lshl_add_u64 v[64:65], s[6:7], 0, v[68:69]
	global_load_dwordx4 v[202:205], v[64:65], off
	s_waitcnt vmcnt(9)
	v_mfma_f32_16x16x32_bf16 v[0:3], v[208:211], v[212:215], v[0:3]
	v_lshl_add_u64 v[64:65], s[6:7], 0, v[70:71]
	global_load_dwordx4 v[208:211], v[64:65], off
	v_lshl_add_u64 v[64:65], s[6:7], 0, v[72:73]
	s_waitcnt vmcnt(7)
	v_mfma_f32_16x16x32_bf16 v[0:3], v[178:181], v[186:189], v[0:3]
	global_load_dwordx4 v[178:181], v[154:155], off
	global_load_dwordx4 v[186:189], v[156:157], off
	s_waitcnt vmcnt(8)
	v_mfma_f32_16x16x32_bf16 v[0:3], v[216:219], v[220:223], v[0:3]
	global_load_dwordx4 v[212:215], v[64:65], off
	global_load_dwordx4 v[216:219], v[158:159], off
	v_lshl_add_u64 v[64:65], s[6:7], 0, v[76:77]
	s_waitcnt vmcnt(8)
	v_mfma_f32_16x16x32_bf16 v[0:3], v[182:185], v[190:193], v[0:3]
	global_load_dwordx4 v[182:185], v[64:65], off
	global_load_dwordx4 v[190:193], v[160:161], off
	v_lshl_add_u64 v[64:65], s[6:7], 0, v[80:81]
	s_waitcnt vmcnt(8)
	v_mfma_f32_16x16x32_bf16 v[0:3], v[198:201], v[194:197], v[0:3]
	s_waitcnt vmcnt(5)
	v_mfma_f32_16x16x32_bf16 v[0:3], v[202:205], v[178:181], v[0:3]
	global_load_dwordx4 v[178:181], v[64:65], off
	v_lshl_add_u64 v[64:65], s[6:7], 0, v[84:85]
	global_load_dwordx4 v[194:197], v[64:65], off
	s_waitcnt vmcnt(6)
	v_mfma_f32_16x16x32_bf16 v[0:3], v[208:211], v[186:189], v[0:3]
	global_load_dwordx4 v[186:189], v[162:163], off
	global_load_dwordx4 v[198:201], v[164:165], off
	v_lshl_add_u64 v[64:65], s[6:7], 0, v[88:89]
	global_load_dwordx4 v[202:205], v[64:65], off
	s_waitcnt vmcnt(7)
	v_mfma_f32_16x16x32_bf16 v[0:3], v[212:215], v[216:219], v[0:3]
	s_waitcnt vmcnt(5)
	v_mfma_f32_16x16x32_bf16 v[0:3], v[182:185], v[190:193], v[0:3]
	global_load_dwordx4 v[182:185], v[166:167], off
	v_lshl_add_u64 v[64:65], s[6:7], 0, v[92:93]
	s_waitcnt vmcnt(3)
	v_mfma_f32_16x16x32_bf16 v[0:3], v[178:181], v[186:189], v[0:3]
	global_load_dwordx4 v[178:181], v[64:65], off
	global_load_dwordx4 v[186:189], v[168:169], off
	v_lshl_add_u64 v[64:65], s[6:7], 0, v[96:97]
	global_load_dwordx4 v[190:193], v[64:65], off
	s_waitcnt vmcnt(5)
	v_mfma_f32_16x16x32_bf16 v[0:3], v[194:197], v[198:201], v[0:3]
	s_waitcnt vmcnt(3)
	v_mfma_f32_16x16x32_bf16 v[0:3], v[202:205], v[182:185], v[0:3]
	global_load_dwordx4 v[182:185], v[170:171], off
	v_lshl_add_u64 v[64:65], s[6:7], 0, v[100:101]
	s_waitcnt vmcnt(2)
	v_mfma_f32_16x16x32_bf16 v[0:3], v[178:181], v[186:189], v[0:3]
	global_load_dwordx4 v[178:181], v[64:65], off
	global_load_dwordx4 v[186:189], v[172:173], off
	v_lshl_add_u64 v[64:65], s[6:7], 0, v[104:105]
	s_waitcnt vmcnt(2)
	v_mfma_f32_16x16x32_bf16 v[0:3], v[190:193], v[182:185], v[0:3]
	global_load_dwordx4 v[182:185], v[64:65], off
	v_add_u32_e32 v64, s10, v176
	s_waitcnt vmcnt(1)
	v_mfma_f32_16x16x32_bf16 v[0:3], v[178:181], v[186:189], v[0:3]
	s_waitcnt vmcnt(0)
	v_mfma_f32_16x16x32_bf16 v[0:3], v[182:185], v[248:251], v[0:3]
	s_nop 7
	ds_write_b128 v64, v[0:3]
	s_waitcnt lgkmcnt(0)
	s_waitcnt lgkmcnt(0)
	s_barrier
	s_cbranch_vccnz .LBB0_405
	ds_read_b128 v[0:3], v176
	ds_read_b128 v[178:181], v176 offset:1024
	ds_read_b128 v[182:185], v176 offset:2048
	ds_read_b128 v[186:189], v176 offset:3072
	s_waitcnt lgkmcnt(2)
	v_pk_add_f32 v[2:3], v[2:3], v[180:181]
	v_pk_add_f32 v[64:65], v[0:1], v[178:179]
	s_waitcnt lgkmcnt(1)
	v_pk_add_f32 v[178:179], v[2:3], v[184:185]
	ds_read_b128 v[0:3], v176 offset:4096
	v_pk_add_f32 v[64:65], v[64:65], v[182:183]
	s_waitcnt lgkmcnt(1)
	v_pk_add_f32 v[182:183], v[178:179], v[188:189]
	ds_read_b128 v[178:181], v176 offset:5120
	v_pk_add_f32 v[64:65], v[64:65], v[186:187]
	s_waitcnt lgkmcnt(1)
	v_pk_add_f32 v[186:187], v[182:183], v[2:3]
	ds_read_b128 v[182:185], v176 offset:6144
	v_pk_add_f32 v[64:65], v[64:65], v[0:1]
	ds_read_b128 v[0:3], v176 offset:7168
	s_waitcnt lgkmcnt(2)
	v_pk_add_f32 v[64:65], v[64:65], v[178:179]
	v_pk_add_f32 v[180:181], v[186:187], v[180:181]
	s_waitcnt lgkmcnt(1)
	v_pk_add_f32 v[64:65], v[64:65], v[182:183]
	v_pk_add_f32 v[178:179], v[180:181], v[184:185]
	s_waitcnt lgkmcnt(0)
	v_pk_add_f32 v[0:1], v[64:65], v[0:1]
	v_pk_add_f32 v[2:3], v[178:179], v[2:3]
	v_bfe_u32 v64, v0, 16, 1
	v_add3_u32 v0, v0, v64, s12
	v_bfe_u32 v64, v1, 16, 1
	v_lshrrev_b32_e32 v0, 16, v0
	v_add3_u32 v1, v1, v64, s12
	v_and_or_b32 v0, v1, s13, v0
	v_bfe_u32 v1, v2, 16, 1
	v_add3_u32 v1, v2, v1, s12
	v_bfe_u32 v2, v3, 16, 1
	v_lshrrev_b32_e32 v1, 16, v1
	v_add3_u32 v2, v3, v2, s12
	v_and_or_b32 v1, v2, s13, v1
	v_lshl_add_u64 v[2:3], s[4:5], 1, v[60:61]
	global_store_dwordx2 v[2:3], v[0:1], off
	s_branch .LBB0_405
.Lsk2_done:
	s_mov_b64 s[4:5], s[90:91]
	v_mbcnt_lo_u32_b32 v0, -1, 0
	v_mbcnt_hi_u32_b32 v0, -1, v0
	s_getreg_b32 s6, hwreg(HW_REG_XCC_ID, 0, 4)
	s_waitcnt vmcnt(0)
	v_sub_u32_e32 v0, 0, v0
	v_cmp_eq_u32_e32 vcc, s74, v0
	s_waitcnt vmcnt(0)
	s_barrier
	s_and_saveexec_b64 s[2:3], vcc
	s_cbranch_execz .LBB0_505
	s_add_i32 s0, 0, 0x22160
	v_mov_b32_e32 v0, s0
	s_load_dwordx2 s[4:5], s[4:5], 0xc8
	s_waitcnt vmcnt(0) expcnt(0) lgkmcnt(0)
	ds_read_b32 v2, v0
	s_add_i32 s0, 0, 0x22164
	v_mov_b32_e32 v0, s0
	ds_read_b32 v1, v0
	s_and_b32 s12, s6, 15
	s_waitcnt lgkmcnt(1)
	v_cmp_ne_u32_e32 vcc, 0, v2
	s_cbranch_vccnz .LBB0_454
	v_readlane_b32 s6, v255, 0
	v_readlane_b32 s7, v255, 1
	s_load_dwordx2 s[0:1], s[6:7], 0x4
	s_add_u32 s6, s4, 0x4200
	s_addc_u32 s7, s5, 0
	s_add_u32 s8, s4, 0x4400
	s_addc_u32 s9, s5, 0
	s_add_u32 s10, s4, 0x4500
	s_addc_u32 s11, s5, 0
	s_add_u32 s14, s4, 0x4600
	s_addc_u32 s15, s5, 0
	s_add_u32 s16, s4, 0x4700
	s_addc_u32 s17, s5, 0
	s_add_u32 s18, s4, 0x4800
	s_addc_u32 s19, s5, 0
	s_add_u32 s20, s4, 0x4900
	s_addc_u32 s21, s5, 0
	s_add_u32 s30, s4, 0x4a00
	s_addc_u32 s31, s5, 0
	s_add_u32 s34, s4, 0x4b00
	s_addc_u32 s35, s5, 0
	s_add_u32 s36, s4, 0x4c00
	s_addc_u32 s37, s5, 0
	s_add_u32 s38, s4, 0x4d00
	s_addc_u32 s39, s5, 0
	s_add_u32 s40, s4, 0x4e00
	s_addc_u32 s41, s5, 0
	s_add_u32 s42, s4, 0x4f00
	s_addc_u32 s43, s5, 0
	s_add_u32 s44, s4, 0x5000
	s_addc_u32 s45, s5, 0
	s_add_u32 s46, s4, 0x5100
	s_addc_u32 s47, s5, 0
	s_add_u32 s48, s4, 0x5200
	s_addc_u32 s49, s5, 0
	s_waitcnt lgkmcnt(0)
	s_mul_i32 s13, s0, s72
	s_add_u32 s50, s4, 0x5300
	s_mul_i32 s13, s13, s1
	s_addc_u32 s51, s5, 0
	s_mov_b32 s23, 1
	v_mov_b32_e32 v16, 0
	s_branch .LBB0_442
